# K loop: wave priority raised during the LDS-read/DMA-issue segment instead of during the MFMA segment
# speedup vs baseline: 1.0039x; 1.0039x over previous
.Llora_n:
	s_add_u32 s10, s78, 0x80
	s_addc_u32 s11, s79, 0
	s_add_u32 s84, s84, 0x100
	s_addc_u32 s85, s85, 0
	s_mov_b32 s78, 0
	s_add_i32 s72, s78, 2
	s_add_u32 s79, s10, 0x80
	s_addc_u32 vcc_lo, s11, 0
	v_add_u32_e32 v148, 0x10000, v185
	s_cmp_eq_u32 s15, s78
	s_cselect_b32 s78, s12, s84
	s_cselect_b32 vcc_hi, s49, vcc_lo
	s_cselect_b32 vcc_lo, s48, s79
	s_cselect_b32 s79, s13, s85
	s_setprio 2
	ds_read_b128 v[128:131], v148 offset:0
	ds_read_b128 v[132:135], v148 offset:1024
	ds_read_b128 v[136:139], v148 offset:2048
	ds_read_b128 v[140:143], v148 offset:3072
	ds_read_b128 v[218:221], v148 offset:16384
	ds_read_b128 v[222:225], v148 offset:17408
	ds_read_b128 v[226:229], v148 offset:18432
	ds_read_b128 v[230:233], v148 offset:19456
	ds_read_b128 v[162:165], v188 offset:0
	ds_read_b128 v[190:193], v188 offset:1024
	ds_read_b128 v[194:197], v188 offset:2048
	ds_read_b128 v[198:201], v188 offset:3072
	ds_read_b128 v[202:205], v188 offset:4096
	ds_read_b128 v[206:209], v188 offset:5120
	ds_read_b128 v[210:213], v188 offset:6144
	ds_read_b128 v[214:217], v188 offset:7168
	s_add_u32 s4, s10, s26
	s_addc_u32 s5, s11, 0
	s_add_i32 m0, s81, 0xc000
	s_nop 0
	global_load_lds_dwordx4 v152, s[4:5]
	s_add_i32 m0, s81, 0xe000
	s_nop 0
	global_load_lds_dwordx4 v144, s[4:5]
	s_setprio 0
	s_waitcnt vmcnt(8)
	s_waitcnt lgkmcnt(0)
	s_barrier
	v_mfma_f32_16x16x32_bf16 v[124:127], v[128:131], v[162:165], 0
	v_mfma_f32_16x16x32_bf16 v[116:119], v[136:139], v[162:165], 0
	v_mfma_f32_16x16x32_bf16 v[120:123], v[128:131], v[194:197], 0
	v_mfma_f32_16x16x32_bf16 v[112:115], v[136:139], v[194:197], 0
	v_mfma_f32_16x16x32_bf16 v[92:95], v[128:131], v[202:205], 0
	v_mfma_f32_16x16x32_bf16 v[84:87], v[136:139], v[202:205], 0
	v_mfma_f32_16x16x32_bf16 v[88:91], v[128:131], v[210:213], 0
	v_mfma_f32_16x16x32_bf16 v[80:83], v[136:139], v[210:213], 0
	v_mfma_f32_16x16x32_bf16 v[124:127], v[132:135], v[190:193], v[124:127]
	v_mfma_f32_16x16x32_bf16 v[116:119], v[140:143], v[190:193], v[116:119]
	v_mfma_f32_16x16x32_bf16 v[120:123], v[132:135], v[198:201], v[120:123]
	v_mfma_f32_16x16x32_bf16 v[112:115], v[140:143], v[198:201], v[112:115]
	v_mfma_f32_16x16x32_bf16 v[92:95], v[132:135], v[206:209], v[92:95]
	v_mfma_f32_16x16x32_bf16 v[84:87], v[140:143], v[206:209], v[84:87]
	v_mfma_f32_16x16x32_bf16 v[88:91], v[132:135], v[214:217], v[88:91]
	v_mfma_f32_16x16x32_bf16 v[80:83], v[140:143], v[214:217], v[80:83]
	v_mfma_f32_16x16x32_bf16 v[108:111], v[218:221], v[162:165], 0
	v_mfma_f32_16x16x32_bf16 v[100:103], v[226:229], v[162:165], 0
	v_mfma_f32_16x16x32_bf16 v[104:107], v[218:221], v[194:197], 0
	v_mfma_f32_16x16x32_bf16 v[96:99], v[226:229], v[194:197], 0
	v_mfma_f32_16x16x32_bf16 v[76:79], v[218:221], v[202:205], 0
	v_mfma_f32_16x16x32_bf16 v[68:71], v[226:229], v[202:205], 0
	v_mfma_f32_16x16x32_bf16 v[72:75], v[218:221], v[210:213], 0
	v_mfma_f32_16x16x32_bf16 v[64:67], v[226:229], v[210:213], 0
	v_mfma_f32_16x16x32_bf16 v[108:111], v[222:225], v[190:193], v[108:111]
	v_mfma_f32_16x16x32_bf16 v[100:103], v[230:233], v[190:193], v[100:103]
	v_mfma_f32_16x16x32_bf16 v[104:107], v[222:225], v[198:201], v[104:107]
	v_mfma_f32_16x16x32_bf16 v[96:99], v[230:233], v[198:201], v[96:99]
	v_mfma_f32_16x16x32_bf16 v[76:79], v[222:225], v[206:209], v[76:79]
	v_mfma_f32_16x16x32_bf16 v[68:71], v[230:233], v[206:209], v[68:71]
	v_mfma_f32_16x16x32_bf16 v[72:75], v[222:225], v[214:217], v[72:75]
	v_mfma_f32_16x16x32_bf16 v[64:67], v[230:233], v[214:217], v[64:67]
	s_barrier
	s_setprio 2
	ds_read_b128 v[162:165], v188 offset:16384
	ds_read_b128 v[190:193], v188 offset:17408
	ds_read_b128 v[194:197], v188 offset:18432
	ds_read_b128 v[198:201], v188 offset:19456
	ds_read_b128 v[202:205], v188 offset:20480
	ds_read_b128 v[206:209], v188 offset:21504
	ds_read_b128 v[210:213], v188 offset:22528
	ds_read_b128 v[214:217], v188 offset:23552
	s_add_i32 m0, s81, 0x10000
	s_nop 0
	global_load_lds_dwordx4 v154, s[78:79]
	s_add_i32 m0, s81, 0x12000
	s_nop 0
	global_load_lds_dwordx4 v146, s[78:79]
	s_add_i32 m0, s81, 0x0
	s_nop 0
	global_load_lds_dwordx4 v152, vcc
	s_add_i32 m0, s81, 0x2000
	s_nop 0
	global_load_lds_dwordx4 v144, vcc
	s_add_u32 s4, s78, s26
	s_addc_u32 s5, s79, 0
	s_add_i32 m0, s81, 0x14000
	s_nop 0
	global_load_lds_dwordx4 v154, s[4:5]
	s_add_i32 m0, s81, 0x16000
	s_nop 0
	global_load_lds_dwordx4 v146, s[4:5]
	s_setprio 0
	s_waitcnt vmcnt(8)
	s_waitcnt lgkmcnt(0)
	s_barrier
	v_mfma_f32_16x16x32_bf16 v[60:63], v[128:131], v[162:165], 0
	v_mfma_f32_16x16x32_bf16 v[56:59], v[136:139], v[162:165], 0
	v_mfma_f32_16x16x32_bf16 v[52:55], v[128:131], v[194:197], 0
	v_mfma_f32_16x16x32_bf16 v[48:51], v[136:139], v[194:197], 0
	v_mfma_f32_16x16x32_bf16 v[28:31], v[128:131], v[202:205], 0
	v_mfma_f32_16x16x32_bf16 v[20:23], v[136:139], v[202:205], 0
	v_mfma_f32_16x16x32_bf16 v[24:27], v[128:131], v[210:213], 0
	v_mfma_f32_16x16x32_bf16 v[16:19], v[136:139], v[210:213], 0
	v_mfma_f32_16x16x32_bf16 v[60:63], v[132:135], v[190:193], v[60:63]
	v_mfma_f32_16x16x32_bf16 v[56:59], v[140:143], v[190:193], v[56:59]
	v_mfma_f32_16x16x32_bf16 v[52:55], v[132:135], v[198:201], v[52:55]
	v_mfma_f32_16x16x32_bf16 v[48:51], v[140:143], v[198:201], v[48:51]
	v_mfma_f32_16x16x32_bf16 v[28:31], v[132:135], v[206:209], v[28:31]
	v_mfma_f32_16x16x32_bf16 v[20:23], v[140:143], v[206:209], v[20:23]
	v_mfma_f32_16x16x32_bf16 v[24:27], v[132:135], v[214:217], v[24:27]
	v_mfma_f32_16x16x32_bf16 v[16:19], v[140:143], v[214:217], v[16:19]
	v_mfma_f32_16x16x32_bf16 v[44:47], v[218:221], v[162:165], 0
	v_mfma_f32_16x16x32_bf16 v[36:39], v[226:229], v[162:165], 0
	v_mfma_f32_16x16x32_bf16 v[40:43], v[218:221], v[194:197], 0
	v_mfma_f32_16x16x32_bf16 v[32:35], v[226:229], v[194:197], 0
	v_mfma_f32_16x16x32_bf16 v[12:15], v[218:221], v[202:205], 0
	v_mfma_f32_16x16x32_bf16 v[4:7], v[226:229], v[202:205], 0
	v_mfma_f32_16x16x32_bf16 v[8:11], v[218:221], v[210:213], 0
	v_mfma_f32_16x16x32_bf16 v[0:3], v[226:229], v[210:213], 0
	v_mfma_f32_16x16x32_bf16 v[44:47], v[222:225], v[190:193], v[44:47]
	v_mfma_f32_16x16x32_bf16 v[36:39], v[230:233], v[190:193], v[36:39]
	v_mfma_f32_16x16x32_bf16 v[40:43], v[222:225], v[198:201], v[40:43]
	v_mfma_f32_16x16x32_bf16 v[32:35], v[230:233], v[198:201], v[32:35]
	v_mfma_f32_16x16x32_bf16 v[12:15], v[222:225], v[206:209], v[12:15]
	v_mfma_f32_16x16x32_bf16 v[4:7], v[230:233], v[206:209], v[4:7]
	v_mfma_f32_16x16x32_bf16 v[8:11], v[222:225], v[214:217], v[8:11]
	v_mfma_f32_16x16x32_bf16 v[0:3], v[230:233], v[214:217], v[0:3]
	s_barrier
	s_setprio 2
	ds_read_b128 v[128:131], v148 offset:32768
	ds_read_b128 v[132:135], v148 offset:33792
	ds_read_b128 v[136:139], v148 offset:34816
	ds_read_b128 v[140:143], v148 offset:35840
	ds_read_b128 v[218:221], v148 offset:49152
	ds_read_b128 v[222:225], v148 offset:50176
	ds_read_b128 v[226:229], v148 offset:51200
	ds_read_b128 v[230:233], v148 offset:52224
	ds_read_b128 v[162:165], v188 offset:32768
	ds_read_b128 v[190:193], v188 offset:33792
	ds_read_b128 v[194:197], v188 offset:34816
	ds_read_b128 v[198:201], v188 offset:35840
	ds_read_b128 v[202:205], v188 offset:36864
	ds_read_b128 v[206:209], v188 offset:37888
	ds_read_b128 v[210:213], v188 offset:38912
	ds_read_b128 v[214:217], v188 offset:39936
	s_add_u32 s4, vcc_lo, s26
	s_addc_u32 s5, vcc_hi, 0
	s_add_i32 m0, s81, 0x4000
	s_nop 0
	global_load_lds_dwordx4 v152, s[4:5]
	s_add_i32 m0, s81, 0x6000
	s_nop 0
	global_load_lds_dwordx4 v144, s[4:5]
	s_setprio 0
	s_waitcnt vmcnt(8)
	s_waitcnt lgkmcnt(0)
	s_barrier
	v_mfma_f32_16x16x32_bf16 v[124:127], v[128:131], v[162:165], v[124:127]
	v_mfma_f32_16x16x32_bf16 v[116:119], v[136:139], v[162:165], v[116:119]
	v_mfma_f32_16x16x32_bf16 v[120:123], v[128:131], v[194:197], v[120:123]
	v_mfma_f32_16x16x32_bf16 v[112:115], v[136:139], v[194:197], v[112:115]
	v_mfma_f32_16x16x32_bf16 v[92:95], v[128:131], v[202:205], v[92:95]
	v_mfma_f32_16x16x32_bf16 v[84:87], v[136:139], v[202:205], v[84:87]
	v_mfma_f32_16x16x32_bf16 v[88:91], v[128:131], v[210:213], v[88:91]
	v_mfma_f32_16x16x32_bf16 v[80:83], v[136:139], v[210:213], v[80:83]
	v_mfma_f32_16x16x32_bf16 v[124:127], v[132:135], v[190:193], v[124:127]
	v_mfma_f32_16x16x32_bf16 v[116:119], v[140:143], v[190:193], v[116:119]
	v_mfma_f32_16x16x32_bf16 v[120:123], v[132:135], v[198:201], v[120:123]
	v_mfma_f32_16x16x32_bf16 v[112:115], v[140:143], v[198:201], v[112:115]
	v_mfma_f32_16x16x32_bf16 v[92:95], v[132:135], v[206:209], v[92:95]
	v_mfma_f32_16x16x32_bf16 v[84:87], v[140:143], v[206:209], v[84:87]
	v_mfma_f32_16x16x32_bf16 v[88:91], v[132:135], v[214:217], v[88:91]
	v_mfma_f32_16x16x32_bf16 v[80:83], v[140:143], v[214:217], v[80:83]
	v_mfma_f32_16x16x32_bf16 v[108:111], v[218:221], v[162:165], v[108:111]
	v_mfma_f32_16x16x32_bf16 v[100:103], v[226:229], v[162:165], v[100:103]
	v_mfma_f32_16x16x32_bf16 v[104:107], v[218:221], v[194:197], v[104:107]
	v_mfma_f32_16x16x32_bf16 v[96:99], v[226:229], v[194:197], v[96:99]
	v_mfma_f32_16x16x32_bf16 v[76:79], v[218:221], v[202:205], v[76:79]
	v_mfma_f32_16x16x32_bf16 v[68:71], v[226:229], v[202:205], v[68:71]
	v_mfma_f32_16x16x32_bf16 v[72:75], v[218:221], v[210:213], v[72:75]
	v_mfma_f32_16x16x32_bf16 v[64:67], v[226:229], v[210:213], v[64:67]
	v_mfma_f32_16x16x32_bf16 v[108:111], v[222:225], v[190:193], v[108:111]
	v_mfma_f32_16x16x32_bf16 v[100:103], v[230:233], v[190:193], v[100:103]
	v_mfma_f32_16x16x32_bf16 v[104:107], v[222:225], v[198:201], v[104:107]
	v_mfma_f32_16x16x32_bf16 v[96:99], v[230:233], v[198:201], v[96:99]
	v_mfma_f32_16x16x32_bf16 v[76:79], v[222:225], v[206:209], v[76:79]
	v_mfma_f32_16x16x32_bf16 v[68:71], v[230:233], v[206:209], v[68:71]
	v_mfma_f32_16x16x32_bf16 v[72:75], v[222:225], v[214:217], v[72:75]
	v_mfma_f32_16x16x32_bf16 v[64:67], v[230:233], v[214:217], v[64:67]
	s_barrier
	s_setprio 2
	ds_read_b128 v[162:165], v188 offset:49152
	ds_read_b128 v[190:193], v188 offset:50176
	ds_read_b128 v[194:197], v188 offset:51200
	ds_read_b128 v[198:201], v188 offset:52224
	ds_read_b128 v[202:205], v188 offset:53248
	ds_read_b128 v[206:209], v188 offset:54272
	ds_read_b128 v[210:213], v188 offset:55296
	ds_read_b128 v[214:217], v188 offset:56320
	s_add_u32 s4, s78, 0x80
	s_addc_u32 s5, s79, 0
	s_add_i32 m0, s81, 0x18000
	s_nop 0
	global_load_lds_dwordx4 v154, s[4:5]
	s_add_i32 m0, s81, 0x1a000
	s_nop 0
	global_load_lds_dwordx4 v146, s[4:5]
	s_add_u32 s4, vcc_lo, 0x80
	s_addc_u32 s5, vcc_hi, 0
	s_add_i32 m0, s81, 0x8000
	s_nop 0
	global_load_lds_dwordx4 v152, s[4:5]
	s_add_i32 m0, s81, 0xa000
	s_nop 0
	global_load_lds_dwordx4 v144, s[4:5]
	s_add_u32 s4, s78, s26
	s_addc_u32 s5, s79, 0
	s_add_u32 s4, s4, 0x80
	s_addc_u32 s5, s5, 0
	s_add_i32 m0, s81, 0x1c000
	s_nop 0
	global_load_lds_dwordx4 v154, s[4:5]
	s_add_i32 m0, s81, 0x1e000
	s_nop 0
	global_load_lds_dwordx4 v146, s[4:5]
	s_setprio 0
	s_waitcnt vmcnt(8)
	s_waitcnt lgkmcnt(0)
	s_barrier
	v_mfma_f32_16x16x32_bf16 v[60:63], v[128:131], v[162:165], v[60:63]
	v_mfma_f32_16x16x32_bf16 v[56:59], v[136:139], v[162:165], v[56:59]
	v_mfma_f32_16x16x32_bf16 v[52:55], v[128:131], v[194:197], v[52:55]
	v_mfma_f32_16x16x32_bf16 v[48:51], v[136:139], v[194:197], v[48:51]
	v_mfma_f32_16x16x32_bf16 v[28:31], v[128:131], v[202:205], v[28:31]
	v_mfma_f32_16x16x32_bf16 v[20:23], v[136:139], v[202:205], v[20:23]
	v_mfma_f32_16x16x32_bf16 v[24:27], v[128:131], v[210:213], v[24:27]
	v_mfma_f32_16x16x32_bf16 v[16:19], v[136:139], v[210:213], v[16:19]
	v_mfma_f32_16x16x32_bf16 v[60:63], v[132:135], v[190:193], v[60:63]
	v_mfma_f32_16x16x32_bf16 v[56:59], v[140:143], v[190:193], v[56:59]
	v_mfma_f32_16x16x32_bf16 v[52:55], v[132:135], v[198:201], v[52:55]
	v_mfma_f32_16x16x32_bf16 v[48:51], v[140:143], v[198:201], v[48:51]
	v_mfma_f32_16x16x32_bf16 v[28:31], v[132:135], v[206:209], v[28:31]
	v_mfma_f32_16x16x32_bf16 v[20:23], v[140:143], v[206:209], v[20:23]
	v_mfma_f32_16x16x32_bf16 v[24:27], v[132:135], v[214:217], v[24:27]
	v_mfma_f32_16x16x32_bf16 v[16:19], v[140:143], v[214:217], v[16:19]
	v_mfma_f32_16x16x32_bf16 v[44:47], v[218:221], v[162:165], v[44:47]
	v_mfma_f32_16x16x32_bf16 v[36:39], v[226:229], v[162:165], v[36:39]
	v_mfma_f32_16x16x32_bf16 v[40:43], v[218:221], v[194:197], v[40:43]
	v_mfma_f32_16x16x32_bf16 v[32:35], v[226:229], v[194:197], v[32:35]
	v_mfma_f32_16x16x32_bf16 v[12:15], v[218:221], v[202:205], v[12:15]
	v_mfma_f32_16x16x32_bf16 v[4:7], v[226:229], v[202:205], v[4:7]
	v_mfma_f32_16x16x32_bf16 v[8:11], v[218:221], v[210:213], v[8:11]
	v_mfma_f32_16x16x32_bf16 v[0:3], v[226:229], v[210:213], v[0:3]
	v_mfma_f32_16x16x32_bf16 v[44:47], v[222:225], v[190:193], v[44:47]
	v_mfma_f32_16x16x32_bf16 v[36:39], v[230:233], v[190:193], v[36:39]
	v_mfma_f32_16x16x32_bf16 v[40:43], v[222:225], v[198:201], v[40:43]
	v_mfma_f32_16x16x32_bf16 v[32:35], v[230:233], v[198:201], v[32:35]
	v_mfma_f32_16x16x32_bf16 v[12:15], v[222:225], v[206:209], v[12:15]
	v_mfma_f32_16x16x32_bf16 v[4:7], v[230:233], v[206:209], v[4:7]
	v_mfma_f32_16x16x32_bf16 v[8:11], v[222:225], v[214:217], v[8:11]
	v_mfma_f32_16x16x32_bf16 v[0:3], v[230:233], v[214:217], v[0:3]
	s_add_u32 s10, s10, 0x100
	s_addc_u32 s11, s11, 0
	s_add_u32 s84, s84, 0x100
	s_addc_u32 s85, s85, 0
	s_cmp_ge_u32 s72, s76
	s_mov_b32 s78, s72
	s_barrier
	s_cbranch_scc1 .Lkloop_done
.LBB0_522:
	s_add_i32 s72, s78, 2
	s_add_u32 s79, s10, 0x80
	s_addc_u32 vcc_lo, s11, 0
	v_add_u32_e32 v148, 0x10000, v185
	s_cmp_eq_u32 s15, s78
	s_cselect_b32 s78, s12, s84
	s_cselect_b32 vcc_hi, s49, vcc_lo
	s_cselect_b32 vcc_lo, s48, s79
	s_cselect_b32 s79, s13, s85
	s_setprio 2
	ds_read_b128 v[128:131], v148 offset:0
	ds_read_b128 v[132:135], v148 offset:1024
	ds_read_b128 v[136:139], v148 offset:2048
	ds_read_b128 v[140:143], v148 offset:3072
	ds_read_b128 v[218:221], v148 offset:16384
	ds_read_b128 v[222:225], v148 offset:17408
	ds_read_b128 v[226:229], v148 offset:18432
	ds_read_b128 v[230:233], v148 offset:19456
	ds_read_b128 v[162:165], v188 offset:0
	ds_read_b128 v[190:193], v188 offset:1024
	ds_read_b128 v[194:197], v188 offset:2048
	ds_read_b128 v[198:201], v188 offset:3072
	ds_read_b128 v[202:205], v188 offset:4096
	ds_read_b128 v[206:209], v188 offset:5120
	ds_read_b128 v[210:213], v188 offset:6144
	ds_read_b128 v[214:217], v188 offset:7168
	s_add_u32 s4, s10, s26
	s_addc_u32 s5, s11, 0
	s_add_i32 m0, s81, 0xc000
	s_nop 0
	global_load_lds_dwordx4 v152, s[4:5]
	s_add_i32 m0, s81, 0xe000
	s_nop 0
	global_load_lds_dwordx4 v144, s[4:5]
	s_setprio 0
	s_waitcnt vmcnt(8)
	s_waitcnt lgkmcnt(0)
	s_barrier
	v_mfma_f32_16x16x32_bf16 v[124:127], v[128:131], v[162:165], v[124:127]
	v_mfma_f32_16x16x32_bf16 v[116:119], v[136:139], v[162:165], v[116:119]
	v_mfma_f32_16x16x32_bf16 v[120:123], v[128:131], v[194:197], v[120:123]
	v_mfma_f32_16x16x32_bf16 v[112:115], v[136:139], v[194:197], v[112:115]
	v_mfma_f32_16x16x32_bf16 v[92:95], v[128:131], v[202:205], v[92:95]
	v_mfma_f32_16x16x32_bf16 v[84:87], v[136:139], v[202:205], v[84:87]
	v_mfma_f32_16x16x32_bf16 v[88:91], v[128:131], v[210:213], v[88:91]
	v_mfma_f32_16x16x32_bf16 v[80:83], v[136:139], v[210:213], v[80:83]
	v_mfma_f32_16x16x32_bf16 v[124:127], v[132:135], v[190:193], v[124:127]
	v_mfma_f32_16x16x32_bf16 v[116:119], v[140:143], v[190:193], v[116:119]
	v_mfma_f32_16x16x32_bf16 v[120:123], v[132:135], v[198:201], v[120:123]
	v_mfma_f32_16x16x32_bf16 v[112:115], v[140:143], v[198:201], v[112:115]
	v_mfma_f32_16x16x32_bf16 v[92:95], v[132:135], v[206:209], v[92:95]
	v_mfma_f32_16x16x32_bf16 v[84:87], v[140:143], v[206:209], v[84:87]
	v_mfma_f32_16x16x32_bf16 v[88:91], v[132:135], v[214:217], v[88:91]
	v_mfma_f32_16x16x32_bf16 v[80:83], v[140:143], v[214:217], v[80:83]
	v_mfma_f32_16x16x32_bf16 v[108:111], v[218:221], v[162:165], v[108:111]
	v_mfma_f32_16x16x32_bf16 v[100:103], v[226:229], v[162:165], v[100:103]
	v_mfma_f32_16x16x32_bf16 v[104:107], v[218:221], v[194:197], v[104:107]
	v_mfma_f32_16x16x32_bf16 v[96:99], v[226:229], v[194:197], v[96:99]
	v_mfma_f32_16x16x32_bf16 v[76:79], v[218:221], v[202:205], v[76:79]
	v_mfma_f32_16x16x32_bf16 v[68:71], v[226:229], v[202:205], v[68:71]
	v_mfma_f32_16x16x32_bf16 v[72:75], v[218:221], v[210:213], v[72:75]
	v_mfma_f32_16x16x32_bf16 v[64:67], v[226:229], v[210:213], v[64:67]
	v_mfma_f32_16x16x32_bf16 v[108:111], v[222:225], v[190:193], v[108:111]
	v_mfma_f32_16x16x32_bf16 v[100:103], v[230:233], v[190:193], v[100:103]
	v_mfma_f32_16x16x32_bf16 v[104:107], v[222:225], v[198:201], v[104:107]
	v_mfma_f32_16x16x32_bf16 v[96:99], v[230:233], v[198:201], v[96:99]
	v_mfma_f32_16x16x32_bf16 v[76:79], v[222:225], v[206:209], v[76:79]
	v_mfma_f32_16x16x32_bf16 v[68:71], v[230:233], v[206:209], v[68:71]
	v_mfma_f32_16x16x32_bf16 v[72:75], v[222:225], v[214:217], v[72:75]
	v_mfma_f32_16x16x32_bf16 v[64:67], v[230:233], v[214:217], v[64:67]
	s_barrier
	s_setprio 2
	ds_read_b128 v[162:165], v188 offset:16384
	ds_read_b128 v[190:193], v188 offset:17408
	ds_read_b128 v[194:197], v188 offset:18432
	ds_read_b128 v[198:201], v188 offset:19456
	ds_read_b128 v[202:205], v188 offset:20480
	ds_read_b128 v[206:209], v188 offset:21504
	ds_read_b128 v[210:213], v188 offset:22528
	ds_read_b128 v[214:217], v188 offset:23552
	s_add_i32 m0, s81, 0x10000
	s_nop 0
	global_load_lds_dwordx4 v154, s[78:79]
	s_add_i32 m0, s81, 0x12000
	s_nop 0
	global_load_lds_dwordx4 v146, s[78:79]
	s_add_i32 m0, s81, 0x0
	s_nop 0
	global_load_lds_dwordx4 v152, vcc
	s_add_i32 m0, s81, 0x2000
	s_nop 0
	global_load_lds_dwordx4 v144, vcc
	s_add_u32 s4, s78, s26
	s_addc_u32 s5, s79, 0
	s_add_i32 m0, s81, 0x14000
	s_nop 0
	global_load_lds_dwordx4 v154, s[4:5]
	s_add_i32 m0, s81, 0x16000
	s_nop 0
	global_load_lds_dwordx4 v146, s[4:5]
	s_setprio 0
	s_waitcnt vmcnt(8)
	s_waitcnt lgkmcnt(0)
	s_barrier
	v_mfma_f32_16x16x32_bf16 v[60:63], v[128:131], v[162:165], v[60:63]
	v_mfma_f32_16x16x32_bf16 v[56:59], v[136:139], v[162:165], v[56:59]
	v_mfma_f32_16x16x32_bf16 v[52:55], v[128:131], v[194:197], v[52:55]
	v_mfma_f32_16x16x32_bf16 v[48:51], v[136:139], v[194:197], v[48:51]
	v_mfma_f32_16x16x32_bf16 v[28:31], v[128:131], v[202:205], v[28:31]
	v_mfma_f32_16x16x32_bf16 v[20:23], v[136:139], v[202:205], v[20:23]
	v_mfma_f32_16x16x32_bf16 v[24:27], v[128:131], v[210:213], v[24:27]
	v_mfma_f32_16x16x32_bf16 v[16:19], v[136:139], v[210:213], v[16:19]
	v_mfma_f32_16x16x32_bf16 v[60:63], v[132:135], v[190:193], v[60:63]
	v_mfma_f32_16x16x32_bf16 v[56:59], v[140:143], v[190:193], v[56:59]
	v_mfma_f32_16x16x32_bf16 v[52:55], v[132:135], v[198:201], v[52:55]
	v_mfma_f32_16x16x32_bf16 v[48:51], v[140:143], v[198:201], v[48:51]
	v_mfma_f32_16x16x32_bf16 v[28:31], v[132:135], v[206:209], v[28:31]
	v_mfma_f32_16x16x32_bf16 v[20:23], v[140:143], v[206:209], v[20:23]
	v_mfma_f32_16x16x32_bf16 v[24:27], v[132:135], v[214:217], v[24:27]
	v_mfma_f32_16x16x32_bf16 v[16:19], v[140:143], v[214:217], v[16:19]
	v_mfma_f32_16x16x32_bf16 v[44:47], v[218:221], v[162:165], v[44:47]
	v_mfma_f32_16x16x32_bf16 v[36:39], v[226:229], v[162:165], v[36:39]
	v_mfma_f32_16x16x32_bf16 v[40:43], v[218:221], v[194:197], v[40:43]
	v_mfma_f32_16x16x32_bf16 v[32:35], v[226:229], v[194:197], v[32:35]
	v_mfma_f32_16x16x32_bf16 v[12:15], v[218:221], v[202:205], v[12:15]
	v_mfma_f32_16x16x32_bf16 v[4:7], v[226:229], v[202:205], v[4:7]
	v_mfma_f32_16x16x32_bf16 v[8:11], v[218:221], v[210:213], v[8:11]
	v_mfma_f32_16x16x32_bf16 v[0:3], v[226:229], v[210:213], v[0:3]
	v_mfma_f32_16x16x32_bf16 v[44:47], v[222:225], v[190:193], v[44:47]
	v_mfma_f32_16x16x32_bf16 v[36:39], v[230:233], v[190:193], v[36:39]
	v_mfma_f32_16x16x32_bf16 v[40:43], v[222:225], v[198:201], v[40:43]
	v_mfma_f32_16x16x32_bf16 v[32:35], v[230:233], v[198:201], v[32:35]
	v_mfma_f32_16x16x32_bf16 v[12:15], v[222:225], v[206:209], v[12:15]
	v_mfma_f32_16x16x32_bf16 v[4:7], v[230:233], v[206:209], v[4:7]
	v_mfma_f32_16x16x32_bf16 v[8:11], v[222:225], v[214:217], v[8:11]
	v_mfma_f32_16x16x32_bf16 v[0:3], v[230:233], v[214:217], v[0:3]
	s_barrier
	s_setprio 2
	ds_read_b128 v[128:131], v148 offset:32768
	ds_read_b128 v[132:135], v148 offset:33792
	ds_read_b128 v[136:139], v148 offset:34816
	ds_read_b128 v[140:143], v148 offset:35840
	ds_read_b128 v[218:221], v148 offset:49152
	ds_read_b128 v[222:225], v148 offset:50176
	ds_read_b128 v[226:229], v148 offset:51200
	ds_read_b128 v[230:233], v148 offset:52224
	ds_read_b128 v[162:165], v188 offset:32768
	ds_read_b128 v[190:193], v188 offset:33792
	ds_read_b128 v[194:197], v188 offset:34816
	ds_read_b128 v[198:201], v188 offset:35840
	ds_read_b128 v[202:205], v188 offset:36864
	ds_read_b128 v[206:209], v188 offset:37888
	ds_read_b128 v[210:213], v188 offset:38912
	ds_read_b128 v[214:217], v188 offset:39936
	s_add_u32 s4, vcc_lo, s26
	s_addc_u32 s5, vcc_hi, 0
	s_add_i32 m0, s81, 0x4000
	s_nop 0
	global_load_lds_dwordx4 v152, s[4:5]
	s_add_i32 m0, s81, 0x6000
	s_nop 0
	global_load_lds_dwordx4 v144, s[4:5]
	s_setprio 0
	s_waitcnt vmcnt(8)
	s_waitcnt lgkmcnt(0)
	s_barrier
	v_mfma_f32_16x16x32_bf16 v[124:127], v[128:131], v[162:165], v[124:127]
	v_mfma_f32_16x16x32_bf16 v[116:119], v[136:139], v[162:165], v[116:119]
	v_mfma_f32_16x16x32_bf16 v[120:123], v[128:131], v[194:197], v[120:123]
	v_mfma_f32_16x16x32_bf16 v[112:115], v[136:139], v[194:197], v[112:115]
	v_mfma_f32_16x16x32_bf16 v[92:95], v[128:131], v[202:205], v[92:95]
	v_mfma_f32_16x16x32_bf16 v[84:87], v[136:139], v[202:205], v[84:87]
	v_mfma_f32_16x16x32_bf16 v[88:91], v[128:131], v[210:213], v[88:91]
	v_mfma_f32_16x16x32_bf16 v[80:83], v[136:139], v[210:213], v[80:83]
	v_mfma_f32_16x16x32_bf16 v[124:127], v[132:135], v[190:193], v[124:127]
	v_mfma_f32_16x16x32_bf16 v[116:119], v[140:143], v[190:193], v[116:119]
	v_mfma_f32_16x16x32_bf16 v[120:123], v[132:135], v[198:201], v[120:123]
	v_mfma_f32_16x16x32_bf16 v[112:115], v[140:143], v[198:201], v[112:115]
	v_mfma_f32_16x16x32_bf16 v[92:95], v[132:135], v[206:209], v[92:95]
	v_mfma_f32_16x16x32_bf16 v[84:87], v[140:143], v[206:209], v[84:87]
	v_mfma_f32_16x16x32_bf16 v[88:91], v[132:135], v[214:217], v[88:91]
	v_mfma_f32_16x16x32_bf16 v[80:83], v[140:143], v[214:217], v[80:83]
	v_mfma_f32_16x16x32_bf16 v[108:111], v[218:221], v[162:165], v[108:111]
	v_mfma_f32_16x16x32_bf16 v[100:103], v[226:229], v[162:165], v[100:103]
	v_mfma_f32_16x16x32_bf16 v[104:107], v[218:221], v[194:197], v[104:107]
	v_mfma_f32_16x16x32_bf16 v[96:99], v[226:229], v[194:197], v[96:99]
	v_mfma_f32_16x16x32_bf16 v[76:79], v[218:221], v[202:205], v[76:79]
	v_mfma_f32_16x16x32_bf16 v[68:71], v[226:229], v[202:205], v[68:71]
	v_mfma_f32_16x16x32_bf16 v[72:75], v[218:221], v[210:213], v[72:75]
	v_mfma_f32_16x16x32_bf16 v[64:67], v[226:229], v[210:213], v[64:67]
	v_mfma_f32_16x16x32_bf16 v[108:111], v[222:225], v[190:193], v[108:111]
	v_mfma_f32_16x16x32_bf16 v[100:103], v[230:233], v[190:193], v[100:103]
	v_mfma_f32_16x16x32_bf16 v[104:107], v[222:225], v[198:201], v[104:107]
	v_mfma_f32_16x16x32_bf16 v[96:99], v[230:233], v[198:201], v[96:99]
	v_mfma_f32_16x16x32_bf16 v[76:79], v[222:225], v[206:209], v[76:79]
	v_mfma_f32_16x16x32_bf16 v[68:71], v[230:233], v[206:209], v[68:71]
	v_mfma_f32_16x16x32_bf16 v[72:75], v[222:225], v[214:217], v[72:75]
	v_mfma_f32_16x16x32_bf16 v[64:67], v[230:233], v[214:217], v[64:67]
	s_barrier
	s_setprio 2
	ds_read_b128 v[162:165], v188 offset:49152
	ds_read_b128 v[190:193], v188 offset:50176
	ds_read_b128 v[194:197], v188 offset:51200
	ds_read_b128 v[198:201], v188 offset:52224
	ds_read_b128 v[202:205], v188 offset:53248
	ds_read_b128 v[206:209], v188 offset:54272
	ds_read_b128 v[210:213], v188 offset:55296
	ds_read_b128 v[214:217], v188 offset:56320
	s_add_u32 s4, s78, 0x80
	s_addc_u32 s5, s79, 0
	s_add_i32 m0, s81, 0x18000
	s_nop 0
	global_load_lds_dwordx4 v154, s[4:5]
	s_add_i32 m0, s81, 0x1a000
	s_nop 0
	global_load_lds_dwordx4 v146, s[4:5]
	s_add_u32 s4, vcc_lo, 0x80
	s_addc_u32 s5, vcc_hi, 0
	s_add_i32 m0, s81, 0x8000
	s_nop 0
	global_load_lds_dwordx4 v152, s[4:5]
	s_add_i32 m0, s81, 0xa000
	s_nop 0
	global_load_lds_dwordx4 v144, s[4:5]
	s_add_u32 s4, s78, s26
	s_addc_u32 s5, s79, 0
	s_add_u32 s4, s4, 0x80
	s_addc_u32 s5, s5, 0
	s_add_i32 m0, s81, 0x1c000
	s_nop 0
	global_load_lds_dwordx4 v154, s[4:5]
	s_add_i32 m0, s81, 0x1e000
	s_nop 0
	global_load_lds_dwordx4 v146, s[4:5]
	s_setprio 0
	s_waitcnt vmcnt(8)
	s_waitcnt lgkmcnt(0)
	s_barrier
	v_mfma_f32_16x16x32_bf16 v[60:63], v[128:131], v[162:165], v[60:63]
	v_mfma_f32_16x16x32_bf16 v[56:59], v[136:139], v[162:165], v[56:59]
	v_mfma_f32_16x16x32_bf16 v[52:55], v[128:131], v[194:197], v[52:55]
	v_mfma_f32_16x16x32_bf16 v[48:51], v[136:139], v[194:197], v[48:51]
	v_mfma_f32_16x16x32_bf16 v[28:31], v[128:131], v[202:205], v[28:31]
	v_mfma_f32_16x16x32_bf16 v[20:23], v[136:139], v[202:205], v[20:23]
	v_mfma_f32_16x16x32_bf16 v[24:27], v[128:131], v[210:213], v[24:27]
	v_mfma_f32_16x16x32_bf16 v[16:19], v[136:139], v[210:213], v[16:19]
	v_mfma_f32_16x16x32_bf16 v[60:63], v[132:135], v[190:193], v[60:63]
	v_mfma_f32_16x16x32_bf16 v[56:59], v[140:143], v[190:193], v[56:59]
	v_mfma_f32_16x16x32_bf16 v[52:55], v[132:135], v[198:201], v[52:55]
	v_mfma_f32_16x16x32_bf16 v[48:51], v[140:143], v[198:201], v[48:51]
	v_mfma_f32_16x16x32_bf16 v[28:31], v[132:135], v[206:209], v[28:31]
	v_mfma_f32_16x16x32_bf16 v[20:23], v[140:143], v[206:209], v[20:23]
	v_mfma_f32_16x16x32_bf16 v[24:27], v[132:135], v[214:217], v[24:27]
	v_mfma_f32_16x16x32_bf16 v[16:19], v[140:143], v[214:217], v[16:19]
	v_mfma_f32_16x16x32_bf16 v[44:47], v[218:221], v[162:165], v[44:47]
	v_mfma_f32_16x16x32_bf16 v[36:39], v[226:229], v[162:165], v[36:39]
	v_mfma_f32_16x16x32_bf16 v[40:43], v[218:221], v[194:197], v[40:43]
	v_mfma_f32_16x16x32_bf16 v[32:35], v[226:229], v[194:197], v[32:35]
	v_mfma_f32_16x16x32_bf16 v[12:15], v[218:221], v[202:205], v[12:15]
	v_mfma_f32_16x16x32_bf16 v[4:7], v[226:229], v[202:205], v[4:7]
	v_mfma_f32_16x16x32_bf16 v[8:11], v[218:221], v[210:213], v[8:11]
	v_mfma_f32_16x16x32_bf16 v[0:3], v[226:229], v[210:213], v[0:3]
	v_mfma_f32_16x16x32_bf16 v[44:47], v[222:225], v[190:193], v[44:47]
	v_mfma_f32_16x16x32_bf16 v[36:39], v[230:233], v[190:193], v[36:39]
	v_mfma_f32_16x16x32_bf16 v[40:43], v[222:225], v[198:201], v[40:43]
	v_mfma_f32_16x16x32_bf16 v[32:35], v[230:233], v[198:201], v[32:35]
	v_mfma_f32_16x16x32_bf16 v[12:15], v[222:225], v[206:209], v[12:15]
	v_mfma_f32_16x16x32_bf16 v[4:7], v[230:233], v[206:209], v[4:7]
	v_mfma_f32_16x16x32_bf16 v[8:11], v[222:225], v[214:217], v[8:11]
	v_mfma_f32_16x16x32_bf16 v[0:3], v[230:233], v[214:217], v[0:3]
	s_add_u32 s10, s10, 0x100
	s_addc_u32 s11, s11, 0
	s_add_u32 s84, s84, 0x100
	s_addc_u32 s85, s85, 0
	s_cmp_ge_u32 s72, s76
	s_mov_b32 s78, s72
	s_barrier
	s_cbranch_scc0 .LBB0_522
